# grid barrier poll loops: s_sleep 3 instead of 1 between polls (spin back-off)
# speedup vs baseline: 1.0063x; 1.0063x over previous
.Lxbs_0:
	global_load_dword v5, v2, s[50:51] offset:1024 sc1
	s_add_i32 s98, s98, 1
	s_waitcnt vmcnt(0)
	v_cmp_ge_u32_e32 vcc, v5, v4
	s_cmp_lt_u32 s98, 0x100000
	s_cbranch_vccnz .Lxbd_0
	s_cbranch_scc0 .Lxbd_0
	s_sleep 3
	s_branch .Lxbs_0
